# MLA unit end: row-sum half exchange by v_permlane32_swap instead of ds_bpermute
# baseline (speedup 1.0000x reference)
; DI unsigned pk2(float lo, float hi) { f32x2_t v = {lo, hi}; bf16x2_t b = __builtin_convertvector(v, bf16x2_t); return __builtin_bit_cast(unsigned, b); }
; DI float lg2(float x) { return __builtin_amdgcn_logf(x); }
; template <int MODE>
; DI void attn_unit(LAS unsigned char* lds, const AttnArgs a) {
;     ...
;     float inv = 1.f;
;     if (MODE != 2) {
;         const float lt = lrow + __shfl_xor(lrow, 32);
;         inv = 1.0f / lt;
;         if (MODE == 3 && hh == 0) a.lse[qtok * a.ldl] = mrow + lg2(lt);
;     }
; #pragma unroll
;     for (int d = 0; d < NDB; ++d)
; #pragma unroll
;         for (int g4 = 0; g4 < 4; ++g4) {
;             u32x2 w; w.x = pk2(o[d][4 * g4] * inv, o[d][4 * g4 + 1] * inv); w.y = pk2(o[d][4 * g4 + 2] * inv, o[d][4 * g4 + 3] * inv);
;             *(u32x2*)(a.O + qtok * a.ldo + d * 32 + 8 * g4 + 4 * hh) = w;
;         }
.LBB0_186:
	s_cmp_lg_u32 s98, 0
	s_cbranch_scc1 .LBB0_187
	s_lshl_b32 s0, s1, 7
	v_readlane_b32 s1, v255, 15
	v_mov_b32_e32 v0, v230
	v_mov_b32_e32 v2, v230
	s_add_u32 s0, s1, s0
	v_readlane_b32 s1, v255, 16
	s_addc_u32 s1, s1, 0
	v_mov_b32_e32 v143, v1
	v_permlane32_swap_b32 v0, v2
	s_waitcnt lgkmcnt(0)
	v_add_f32_e32 v0, v0, v2
	v_div_scale_f32 v2, s[4:5], v0, v0, 1.0
	v_rcp_f32_e32 v3, v2
	v_readlane_b32 s12, v255, 21
	v_readlane_b32 s13, v255, 22
	v_fma_f32 v4, -v2, v3, 1.0
	v_fmac_f32_e32 v3, v4, v3
	v_div_scale_f32 v4, vcc, 1.0, v0, 1.0
	v_mul_f32_e32 v5, v4, v3
	v_fma_f32 v6, -v2, v5, v4
	v_fmac_f32_e32 v5, v6, v3
	v_fma_f32 v2, -v2, v5, v4
	v_div_fmas_f32 v2, v2, v3, v5
	v_div_fixup_f32 v0, v2, v0, 1.0
	v_lshlrev_b64 v[2:3], 10, v[132:133]
	v_lshl_add_u64 v[2:3], s[0:1], 0, v[2:3]
	v_pk_mul_f32 v[4:5], v[32:33], v[0:1] op_sel_hi:[1,0]
	v_pk_mul_f32 v[6:7], v[34:35], v[0:1] op_sel_hi:[1,0]
	v_lshl_add_u64 v[2:3], v[142:143], 1, v[2:3]
	v_cvt_pk_bf16_f32 v4, v4, v5
	v_cvt_pk_bf16_f32 v5, v6, v7
	global_store_dwordx2 v[2:3], v[4:5], off
	v_pk_mul_f32 v[4:5], v[36:37], v[0:1] op_sel_hi:[1,0]
	v_pk_mul_f32 v[6:7], v[38:39], v[0:1] op_sel_hi:[1,0]
	v_cvt_pk_bf16_f32 v4, v4, v5
	v_cvt_pk_bf16_f32 v5, v6, v7
	global_store_dwordx2 v[2:3], v[4:5], off offset:16
	v_pk_mul_f32 v[4:5], v[40:41], v[0:1] op_sel_hi:[1,0]
	v_pk_mul_f32 v[6:7], v[42:43], v[0:1] op_sel_hi:[1,0]
	v_cvt_pk_bf16_f32 v4, v4, v5
	v_cvt_pk_bf16_f32 v5, v6, v7
	global_store_dwordx2 v[2:3], v[4:5], off offset:32
	v_pk_mul_f32 v[4:5], v[44:45], v[0:1] op_sel_hi:[1,0]
	v_pk_mul_f32 v[6:7], v[46:47], v[0:1] op_sel_hi:[1,0]
	v_cvt_pk_bf16_f32 v4, v4, v5
	v_cvt_pk_bf16_f32 v5, v6, v7
	global_store_dwordx2 v[2:3], v[4:5], off offset:48
	v_pk_mul_f32 v[4:5], v[16:17], v[0:1] op_sel_hi:[1,0]
	v_pk_mul_f32 v[6:7], v[18:19], v[0:1] op_sel_hi:[1,0]
	v_cvt_pk_bf16_f32 v4, v4, v5
	v_cvt_pk_bf16_f32 v5, v6, v7
	global_store_dwordx2 v[2:3], v[4:5], off offset:64
	v_pk_mul_f32 v[4:5], v[20:21], v[0:1] op_sel_hi:[1,0]
	v_pk_mul_f32 v[6:7], v[22:23], v[0:1] op_sel_hi:[1,0]
	v_cvt_pk_bf16_f32 v4, v4, v5
	v_cvt_pk_bf16_f32 v5, v6, v7
	global_store_dwordx2 v[2:3], v[4:5], off offset:80
	v_pk_mul_f32 v[4:5], v[24:25], v[0:1] op_sel_hi:[1,0]
	v_pk_mul_f32 v[6:7], v[26:27], v[0:1] op_sel_hi:[1,0]
	v_cvt_pk_bf16_f32 v4, v4, v5
	v_cvt_pk_bf16_f32 v5, v6, v7
	global_store_dwordx2 v[2:3], v[4:5], off offset:96
	v_pk_mul_f32 v[4:5], v[28:29], v[0:1] op_sel_hi:[1,0]
	v_pk_mul_f32 v[6:7], v[30:31], v[0:1] op_sel_hi:[1,0]
	v_cvt_pk_bf16_f32 v4, v4, v5
	v_cvt_pk_bf16_f32 v5, v6, v7
	global_store_dwordx2 v[2:3], v[4:5], off offset:112
